# P4 epilogue stores made quad-contiguous through a per-wave LDS transpose (row-major lane mapping)
# baseline (speedup 1.0000x reference)
.Lp4_noload:
	v_mbcnt_lo_u32_b32 v196, -1, 0
	v_mbcnt_hi_u32_b32 v196, -1, v196
	v_lshrrev_b32_e32 v197, 2, v196
	v_and_b32_e32 v198, 3, v196
	v_lshlrev_b32_e32 v198, 4, v198
	v_and_b32_e32 v199, 64, v150
	v_add_u32_e32 v199, v199, v197
	v_lshl_add_u32 v188, s30, 8, v199
	v_mov_b64_e32 v[146:147], s[10:11]
	v_mad_i64_i32 v[146:147], s[40:41], v188, s49, v[146:147]
	s_lshl_b32 s20, s31, 8
	s_mov_b32 s21, 0
	s_mov_b64 s[52:53], 0x16000
	s_mov_b64 s[54:55], 0x6e000
	v_lshl_add_u64 v[146:147], v[146:147], 0, s[20:21]
	v_lshl_add_u64 v[146:147], v[146:147], 0, s[4:5]
	v_mov_b32_e32 v199, 0
	v_lshl_add_u64 v[146:147], v[146:147], 0, v[198:199]
	s_lshl_b32 s40, s27, 1
	s_add_i32 s40, s40, 0x20000
	v_and_b32_e32 v208, 15, v196
	v_mul_u32_u24_e32 v208, 0x50, v208
	v_lshrrev_b32_e32 v209, 4, v196
	v_lshl_add_u32 v208, v209, 4, v208
	v_add_u32_e32 v208, s40, v208
	v_mul_u32_u24_e32 v209, 0x50, v197
	v_add3_u32 v209, v209, v198, s40
	v_pk_mul_f32 v[124:125], v[124:125], v[226:227] op_sel_hi:[1,0]
	v_pk_mul_f32 v[116:117], v[116:117], v[226:227] op_sel_hi:[1,0]
	v_pk_mul_f32 v[126:127], v[126:127], v[226:227] op_sel_hi:[1,0]
	v_pk_mul_f32 v[118:119], v[118:119], v[226:227] op_sel_hi:[1,0]
	v_pk_mul_f32 v[120:121], v[120:121], v[226:227] op_sel_hi:[1,0]
	v_pk_mul_f32 v[112:113], v[112:113], v[226:227] op_sel_hi:[1,0]
	v_pk_mul_f32 v[122:123], v[122:123], v[226:227] op_sel_hi:[1,0]
	v_pk_mul_f32 v[114:115], v[114:115], v[226:227] op_sel_hi:[1,0]
	v_mul_f32_e32 v188, 0xbfb8aa3b, v124
	v_mul_f32_e32 v189, 0xbfb8aa3b, v125
	v_mul_f32_e32 v190, 0xbfb8aa3b, v126
	v_mul_f32_e32 v191, 0xbfb8aa3b, v127
	v_mul_f32_e32 v192, 0xbfb8aa3b, v120
	v_mul_f32_e32 v193, 0xbfb8aa3b, v121
	v_mul_f32_e32 v194, 0xbfb8aa3b, v122
	v_mul_f32_e32 v195, 0xbfb8aa3b, v123
	v_pk_mul_f32 v[116:117], v[124:125], v[116:117]
	v_pk_mul_f32 v[118:119], v[126:127], v[118:119]
	v_pk_mul_f32 v[112:113], v[120:121], v[112:113]
	v_pk_mul_f32 v[114:115], v[122:123], v[114:115]
	v_exp_f32_e32 v188, v188
	v_exp_f32_e32 v189, v189
	v_exp_f32_e32 v190, v190
	v_exp_f32_e32 v191, v191
	v_exp_f32_e32 v192, v192
	v_exp_f32_e32 v193, v193
	v_exp_f32_e32 v194, v194
	v_exp_f32_e32 v195, v195
	v_add_f32_e32 v188, 1.0, v188
	v_add_f32_e32 v189, 1.0, v189
	v_add_f32_e32 v190, 1.0, v190
	v_add_f32_e32 v191, 1.0, v191
	v_add_f32_e32 v192, 1.0, v192
	v_add_f32_e32 v193, 1.0, v193
	v_add_f32_e32 v194, 1.0, v194
	v_add_f32_e32 v195, 1.0, v195
	v_rcp_f32_e32 v124, v188
	v_rcp_f32_e32 v125, v189
	v_rcp_f32_e32 v126, v190
	v_rcp_f32_e32 v127, v191
	v_rcp_f32_e32 v120, v192
	v_rcp_f32_e32 v121, v193
	v_rcp_f32_e32 v122, v194
	v_rcp_f32_e32 v123, v195
	v_pk_mul_f32 v[116:117], v[116:117], v[124:125]
	v_pk_mul_f32 v[118:119], v[118:119], v[126:127]
	v_pk_mul_f32 v[112:113], v[112:113], v[120:121]
	v_pk_mul_f32 v[114:115], v[114:115], v[122:123]
	v_cvt_pk_bf16_f32 v124, v116, v117
	v_cvt_pk_bf16_f32 v125, v118, v119
	v_cvt_pk_bf16_f32 v126, v112, v113
	v_cvt_pk_bf16_f32 v127, v114, v115
	ds_write_b128 v208, v[124:127]
	ds_read_b128 v[200:203], v209
	v_pk_mul_f32 v[108:109], v[108:109], v[228:229] op_sel_hi:[1,0]
	v_pk_mul_f32 v[100:101], v[100:101], v[228:229] op_sel_hi:[1,0]
	v_pk_mul_f32 v[110:111], v[110:111], v[228:229] op_sel_hi:[1,0]
	v_pk_mul_f32 v[102:103], v[102:103], v[228:229] op_sel_hi:[1,0]
	v_pk_mul_f32 v[104:105], v[104:105], v[228:229] op_sel_hi:[1,0]
	v_pk_mul_f32 v[96:97], v[96:97], v[228:229] op_sel_hi:[1,0]
	v_pk_mul_f32 v[106:107], v[106:107], v[228:229] op_sel_hi:[1,0]
	v_pk_mul_f32 v[98:99], v[98:99], v[228:229] op_sel_hi:[1,0]
	v_mul_f32_e32 v188, 0xbfb8aa3b, v108
	v_mul_f32_e32 v189, 0xbfb8aa3b, v109
	v_mul_f32_e32 v190, 0xbfb8aa3b, v110
	v_mul_f32_e32 v191, 0xbfb8aa3b, v111
	v_mul_f32_e32 v192, 0xbfb8aa3b, v104
	v_mul_f32_e32 v193, 0xbfb8aa3b, v105
	v_mul_f32_e32 v194, 0xbfb8aa3b, v106
	v_mul_f32_e32 v195, 0xbfb8aa3b, v107
	v_pk_mul_f32 v[100:101], v[108:109], v[100:101]
	v_pk_mul_f32 v[102:103], v[110:111], v[102:103]
	v_pk_mul_f32 v[96:97], v[104:105], v[96:97]
	v_pk_mul_f32 v[98:99], v[106:107], v[98:99]
	v_exp_f32_e32 v188, v188
	v_exp_f32_e32 v189, v189
	v_exp_f32_e32 v190, v190
	v_exp_f32_e32 v191, v191
	v_exp_f32_e32 v192, v192
	v_exp_f32_e32 v193, v193
	v_exp_f32_e32 v194, v194
	v_exp_f32_e32 v195, v195
	v_add_f32_e32 v188, 1.0, v188
	v_add_f32_e32 v189, 1.0, v189
	v_add_f32_e32 v190, 1.0, v190
	v_add_f32_e32 v191, 1.0, v191
	v_add_f32_e32 v192, 1.0, v192
	v_add_f32_e32 v193, 1.0, v193
	v_add_f32_e32 v194, 1.0, v194
	v_add_f32_e32 v195, 1.0, v195
	v_rcp_f32_e32 v108, v188
	v_rcp_f32_e32 v109, v189
	v_rcp_f32_e32 v110, v190
	v_rcp_f32_e32 v111, v191
	v_rcp_f32_e32 v104, v192
	v_rcp_f32_e32 v105, v193
	v_rcp_f32_e32 v106, v194
	v_rcp_f32_e32 v107, v195
	v_pk_mul_f32 v[100:101], v[100:101], v[108:109]
	v_pk_mul_f32 v[102:103], v[102:103], v[110:111]
	v_pk_mul_f32 v[96:97], v[96:97], v[104:105]
	v_pk_mul_f32 v[98:99], v[98:99], v[106:107]
	v_cvt_pk_bf16_f32 v108, v100, v101
	v_cvt_pk_bf16_f32 v109, v102, v103
	v_cvt_pk_bf16_f32 v110, v96, v97
	v_cvt_pk_bf16_f32 v111, v98, v99
	ds_write_b128 v208, v[108:111]
	ds_read_b128 v[204:207], v209
	s_waitcnt lgkmcnt(2)
	global_store_dwordx4 v[146:147], v[200:203], off
	v_lshl_add_u64 v[146:147], v[146:147], 0, s[52:53]
	v_pk_mul_f32 v[92:93], v[92:93], v[230:231] op_sel_hi:[1,0]
	v_pk_mul_f32 v[84:85], v[84:85], v[230:231] op_sel_hi:[1,0]
	v_pk_mul_f32 v[94:95], v[94:95], v[230:231] op_sel_hi:[1,0]
	v_pk_mul_f32 v[86:87], v[86:87], v[230:231] op_sel_hi:[1,0]
	v_pk_mul_f32 v[88:89], v[88:89], v[230:231] op_sel_hi:[1,0]
	v_pk_mul_f32 v[80:81], v[80:81], v[230:231] op_sel_hi:[1,0]
	v_pk_mul_f32 v[90:91], v[90:91], v[230:231] op_sel_hi:[1,0]
	v_pk_mul_f32 v[82:83], v[82:83], v[230:231] op_sel_hi:[1,0]
	v_mul_f32_e32 v188, 0xbfb8aa3b, v92
	v_mul_f32_e32 v189, 0xbfb8aa3b, v93
	v_mul_f32_e32 v190, 0xbfb8aa3b, v94
	v_mul_f32_e32 v191, 0xbfb8aa3b, v95
	v_mul_f32_e32 v192, 0xbfb8aa3b, v88
	v_mul_f32_e32 v193, 0xbfb8aa3b, v89
	v_mul_f32_e32 v194, 0xbfb8aa3b, v90
	v_mul_f32_e32 v195, 0xbfb8aa3b, v91
	v_pk_mul_f32 v[84:85], v[92:93], v[84:85]
	v_pk_mul_f32 v[86:87], v[94:95], v[86:87]
	v_pk_mul_f32 v[80:81], v[88:89], v[80:81]
	v_pk_mul_f32 v[82:83], v[90:91], v[82:83]
	v_exp_f32_e32 v188, v188
	v_exp_f32_e32 v189, v189
	v_exp_f32_e32 v190, v190
	v_exp_f32_e32 v191, v191
	v_exp_f32_e32 v192, v192
	v_exp_f32_e32 v193, v193
	v_exp_f32_e32 v194, v194
	v_exp_f32_e32 v195, v195
	v_add_f32_e32 v188, 1.0, v188
	v_add_f32_e32 v189, 1.0, v189
	v_add_f32_e32 v190, 1.0, v190
	v_add_f32_e32 v191, 1.0, v191
	v_add_f32_e32 v192, 1.0, v192
	v_add_f32_e32 v193, 1.0, v193
	v_add_f32_e32 v194, 1.0, v194
	v_add_f32_e32 v195, 1.0, v195
	v_rcp_f32_e32 v92, v188
	v_rcp_f32_e32 v93, v189
	v_rcp_f32_e32 v94, v190
	v_rcp_f32_e32 v95, v191
	v_rcp_f32_e32 v88, v192
	v_rcp_f32_e32 v89, v193
	v_rcp_f32_e32 v90, v194
	v_rcp_f32_e32 v91, v195
	v_pk_mul_f32 v[84:85], v[84:85], v[92:93]
	v_pk_mul_f32 v[86:87], v[86:87], v[94:95]
	v_pk_mul_f32 v[80:81], v[80:81], v[88:89]
	v_pk_mul_f32 v[82:83], v[82:83], v[90:91]
	v_cvt_pk_bf16_f32 v92, v84, v85
	v_cvt_pk_bf16_f32 v93, v86, v87
	v_cvt_pk_bf16_f32 v94, v80, v81
	v_cvt_pk_bf16_f32 v95, v82, v83
	ds_write_b128 v208, v[92:95]
	ds_read_b128 v[200:203], v209
	s_waitcnt lgkmcnt(2)
	global_store_dwordx4 v[146:147], v[204:207], off
	v_lshl_add_u64 v[146:147], v[146:147], 0, s[52:53]
	v_pk_mul_f32 v[76:77], v[76:77], v[232:233] op_sel_hi:[1,0]
	v_pk_mul_f32 v[68:69], v[68:69], v[232:233] op_sel_hi:[1,0]
	v_pk_mul_f32 v[78:79], v[78:79], v[232:233] op_sel_hi:[1,0]
	v_pk_mul_f32 v[70:71], v[70:71], v[232:233] op_sel_hi:[1,0]
	v_pk_mul_f32 v[72:73], v[72:73], v[232:233] op_sel_hi:[1,0]
	v_pk_mul_f32 v[64:65], v[64:65], v[232:233] op_sel_hi:[1,0]
	v_pk_mul_f32 v[74:75], v[74:75], v[232:233] op_sel_hi:[1,0]
	v_pk_mul_f32 v[66:67], v[66:67], v[232:233] op_sel_hi:[1,0]
	v_mul_f32_e32 v188, 0xbfb8aa3b, v76
	v_mul_f32_e32 v189, 0xbfb8aa3b, v77
	v_mul_f32_e32 v190, 0xbfb8aa3b, v78
	v_mul_f32_e32 v191, 0xbfb8aa3b, v79
	v_mul_f32_e32 v192, 0xbfb8aa3b, v72
	v_mul_f32_e32 v193, 0xbfb8aa3b, v73
	v_mul_f32_e32 v194, 0xbfb8aa3b, v74
	v_mul_f32_e32 v195, 0xbfb8aa3b, v75
	v_pk_mul_f32 v[68:69], v[76:77], v[68:69]
	v_pk_mul_f32 v[70:71], v[78:79], v[70:71]
	v_pk_mul_f32 v[64:65], v[72:73], v[64:65]
	v_pk_mul_f32 v[66:67], v[74:75], v[66:67]
	v_exp_f32_e32 v188, v188
	v_exp_f32_e32 v189, v189
	v_exp_f32_e32 v190, v190
	v_exp_f32_e32 v191, v191
	v_exp_f32_e32 v192, v192
	v_exp_f32_e32 v193, v193
	v_exp_f32_e32 v194, v194
	v_exp_f32_e32 v195, v195
	v_add_f32_e32 v188, 1.0, v188
	v_add_f32_e32 v189, 1.0, v189
	v_add_f32_e32 v190, 1.0, v190
	v_add_f32_e32 v191, 1.0, v191
	v_add_f32_e32 v192, 1.0, v192
	v_add_f32_e32 v193, 1.0, v193
	v_add_f32_e32 v194, 1.0, v194
	v_add_f32_e32 v195, 1.0, v195
	v_rcp_f32_e32 v76, v188
	v_rcp_f32_e32 v77, v189
	v_rcp_f32_e32 v78, v190
	v_rcp_f32_e32 v79, v191
	v_rcp_f32_e32 v72, v192
	v_rcp_f32_e32 v73, v193
	v_rcp_f32_e32 v74, v194
	v_rcp_f32_e32 v75, v195
	v_pk_mul_f32 v[68:69], v[68:69], v[76:77]
	v_pk_mul_f32 v[70:71], v[70:71], v[78:79]
	v_pk_mul_f32 v[64:65], v[64:65], v[72:73]
	v_pk_mul_f32 v[66:67], v[66:67], v[74:75]
	v_cvt_pk_bf16_f32 v76, v68, v69
	v_cvt_pk_bf16_f32 v77, v70, v71
	v_cvt_pk_bf16_f32 v78, v64, v65
	v_cvt_pk_bf16_f32 v79, v66, v67
	ds_write_b128 v208, v[76:79]
	ds_read_b128 v[204:207], v209
	s_waitcnt lgkmcnt(2)
	global_store_dwordx4 v[146:147], v[200:203], off
	v_lshl_add_u64 v[146:147], v[146:147], 0, s[52:53]
	v_pk_mul_f32 v[60:61], v[60:61], v[234:235] op_sel_hi:[1,0]
	v_pk_mul_f32 v[52:53], v[52:53], v[234:235] op_sel_hi:[1,0]
	v_pk_mul_f32 v[62:63], v[62:63], v[234:235] op_sel_hi:[1,0]
	v_pk_mul_f32 v[54:55], v[54:55], v[234:235] op_sel_hi:[1,0]
	v_pk_mul_f32 v[56:57], v[56:57], v[234:235] op_sel_hi:[1,0]
	v_pk_mul_f32 v[48:49], v[48:49], v[234:235] op_sel_hi:[1,0]
	v_pk_mul_f32 v[58:59], v[58:59], v[234:235] op_sel_hi:[1,0]
	v_pk_mul_f32 v[50:51], v[50:51], v[234:235] op_sel_hi:[1,0]
	v_mul_f32_e32 v188, 0xbfb8aa3b, v60
	v_mul_f32_e32 v189, 0xbfb8aa3b, v61
	v_mul_f32_e32 v190, 0xbfb8aa3b, v62
	v_mul_f32_e32 v191, 0xbfb8aa3b, v63
	v_mul_f32_e32 v192, 0xbfb8aa3b, v56
	v_mul_f32_e32 v193, 0xbfb8aa3b, v57
	v_mul_f32_e32 v194, 0xbfb8aa3b, v58
	v_mul_f32_e32 v195, 0xbfb8aa3b, v59
	v_pk_mul_f32 v[52:53], v[60:61], v[52:53]
	v_pk_mul_f32 v[54:55], v[62:63], v[54:55]
	v_pk_mul_f32 v[48:49], v[56:57], v[48:49]
	v_pk_mul_f32 v[50:51], v[58:59], v[50:51]
	v_exp_f32_e32 v188, v188
	v_exp_f32_e32 v189, v189
	v_exp_f32_e32 v190, v190
	v_exp_f32_e32 v191, v191
	v_exp_f32_e32 v192, v192
	v_exp_f32_e32 v193, v193
	v_exp_f32_e32 v194, v194
	v_exp_f32_e32 v195, v195
	v_add_f32_e32 v188, 1.0, v188
	v_add_f32_e32 v189, 1.0, v189
	v_add_f32_e32 v190, 1.0, v190
	v_add_f32_e32 v191, 1.0, v191
	v_add_f32_e32 v192, 1.0, v192
	v_add_f32_e32 v193, 1.0, v193
	v_add_f32_e32 v194, 1.0, v194
	v_add_f32_e32 v195, 1.0, v195
	v_rcp_f32_e32 v60, v188
	v_rcp_f32_e32 v61, v189
	v_rcp_f32_e32 v62, v190
	v_rcp_f32_e32 v63, v191
	v_rcp_f32_e32 v56, v192
	v_rcp_f32_e32 v57, v193
	v_rcp_f32_e32 v58, v194
	v_rcp_f32_e32 v59, v195
	v_pk_mul_f32 v[52:53], v[52:53], v[60:61]
	v_pk_mul_f32 v[54:55], v[54:55], v[62:63]
	v_pk_mul_f32 v[48:49], v[48:49], v[56:57]
	v_pk_mul_f32 v[50:51], v[50:51], v[58:59]
	v_cvt_pk_bf16_f32 v60, v52, v53
	v_cvt_pk_bf16_f32 v61, v54, v55
	v_cvt_pk_bf16_f32 v62, v48, v49
	v_cvt_pk_bf16_f32 v63, v50, v51
	ds_write_b128 v208, v[60:63]
	ds_read_b128 v[200:203], v209
	s_waitcnt lgkmcnt(2)
	global_store_dwordx4 v[146:147], v[204:207], off
	v_lshl_add_u64 v[146:147], v[146:147], 0, s[54:55]
	v_pk_mul_f32 v[44:45], v[44:45], v[236:237] op_sel_hi:[1,0]
	v_pk_mul_f32 v[36:37], v[36:37], v[236:237] op_sel_hi:[1,0]
	v_pk_mul_f32 v[46:47], v[46:47], v[236:237] op_sel_hi:[1,0]
	v_pk_mul_f32 v[38:39], v[38:39], v[236:237] op_sel_hi:[1,0]
	v_pk_mul_f32 v[40:41], v[40:41], v[236:237] op_sel_hi:[1,0]
	v_pk_mul_f32 v[32:33], v[32:33], v[236:237] op_sel_hi:[1,0]
	v_pk_mul_f32 v[42:43], v[42:43], v[236:237] op_sel_hi:[1,0]
	v_pk_mul_f32 v[34:35], v[34:35], v[236:237] op_sel_hi:[1,0]
	v_mul_f32_e32 v188, 0xbfb8aa3b, v44
	v_mul_f32_e32 v189, 0xbfb8aa3b, v45
	v_mul_f32_e32 v190, 0xbfb8aa3b, v46
	v_mul_f32_e32 v191, 0xbfb8aa3b, v47
	v_mul_f32_e32 v192, 0xbfb8aa3b, v40
	v_mul_f32_e32 v193, 0xbfb8aa3b, v41
	v_mul_f32_e32 v194, 0xbfb8aa3b, v42
	v_mul_f32_e32 v195, 0xbfb8aa3b, v43
	v_pk_mul_f32 v[36:37], v[44:45], v[36:37]
	v_pk_mul_f32 v[38:39], v[46:47], v[38:39]
	v_pk_mul_f32 v[32:33], v[40:41], v[32:33]
	v_pk_mul_f32 v[34:35], v[42:43], v[34:35]
	v_exp_f32_e32 v188, v188
	v_exp_f32_e32 v189, v189
	v_exp_f32_e32 v190, v190
	v_exp_f32_e32 v191, v191
	v_exp_f32_e32 v192, v192
	v_exp_f32_e32 v193, v193
	v_exp_f32_e32 v194, v194
	v_exp_f32_e32 v195, v195
	v_add_f32_e32 v188, 1.0, v188
	v_add_f32_e32 v189, 1.0, v189
	v_add_f32_e32 v190, 1.0, v190
	v_add_f32_e32 v191, 1.0, v191
	v_add_f32_e32 v192, 1.0, v192
	v_add_f32_e32 v193, 1.0, v193
	v_add_f32_e32 v194, 1.0, v194
	v_add_f32_e32 v195, 1.0, v195
	v_rcp_f32_e32 v44, v188
	v_rcp_f32_e32 v45, v189
	v_rcp_f32_e32 v46, v190
	v_rcp_f32_e32 v47, v191
	v_rcp_f32_e32 v40, v192
	v_rcp_f32_e32 v41, v193
	v_rcp_f32_e32 v42, v194
	v_rcp_f32_e32 v43, v195
	v_pk_mul_f32 v[36:37], v[36:37], v[44:45]
	v_pk_mul_f32 v[38:39], v[38:39], v[46:47]
	v_pk_mul_f32 v[32:33], v[32:33], v[40:41]
	v_pk_mul_f32 v[34:35], v[34:35], v[42:43]
	v_cvt_pk_bf16_f32 v44, v36, v37
	v_cvt_pk_bf16_f32 v45, v38, v39
	v_cvt_pk_bf16_f32 v46, v32, v33
	v_cvt_pk_bf16_f32 v47, v34, v35
	ds_write_b128 v208, v[44:47]
	ds_read_b128 v[204:207], v209
	s_waitcnt lgkmcnt(2)
	global_store_dwordx4 v[146:147], v[200:203], off
	v_lshl_add_u64 v[146:147], v[146:147], 0, s[52:53]
	v_pk_mul_f32 v[28:29], v[28:29], v[238:239] op_sel_hi:[1,0]
	v_pk_mul_f32 v[20:21], v[20:21], v[238:239] op_sel_hi:[1,0]
	v_pk_mul_f32 v[30:31], v[30:31], v[238:239] op_sel_hi:[1,0]
	v_pk_mul_f32 v[22:23], v[22:23], v[238:239] op_sel_hi:[1,0]
	v_pk_mul_f32 v[24:25], v[24:25], v[238:239] op_sel_hi:[1,0]
	v_pk_mul_f32 v[16:17], v[16:17], v[238:239] op_sel_hi:[1,0]
	v_pk_mul_f32 v[26:27], v[26:27], v[238:239] op_sel_hi:[1,0]
	v_pk_mul_f32 v[18:19], v[18:19], v[238:239] op_sel_hi:[1,0]
	v_mul_f32_e32 v188, 0xbfb8aa3b, v28
	v_mul_f32_e32 v189, 0xbfb8aa3b, v29
	v_mul_f32_e32 v190, 0xbfb8aa3b, v30
	v_mul_f32_e32 v191, 0xbfb8aa3b, v31
	v_mul_f32_e32 v192, 0xbfb8aa3b, v24
	v_mul_f32_e32 v193, 0xbfb8aa3b, v25
	v_mul_f32_e32 v194, 0xbfb8aa3b, v26
	v_mul_f32_e32 v195, 0xbfb8aa3b, v27
	v_pk_mul_f32 v[20:21], v[28:29], v[20:21]
	v_pk_mul_f32 v[22:23], v[30:31], v[22:23]
	v_pk_mul_f32 v[16:17], v[24:25], v[16:17]
	v_pk_mul_f32 v[18:19], v[26:27], v[18:19]
	v_exp_f32_e32 v188, v188
	v_exp_f32_e32 v189, v189
	v_exp_f32_e32 v190, v190
	v_exp_f32_e32 v191, v191
	v_exp_f32_e32 v192, v192
	v_exp_f32_e32 v193, v193
	v_exp_f32_e32 v194, v194
	v_exp_f32_e32 v195, v195
	v_add_f32_e32 v188, 1.0, v188
	v_add_f32_e32 v189, 1.0, v189
	v_add_f32_e32 v190, 1.0, v190
	v_add_f32_e32 v191, 1.0, v191
	v_add_f32_e32 v192, 1.0, v192
	v_add_f32_e32 v193, 1.0, v193
	v_add_f32_e32 v194, 1.0, v194
	v_add_f32_e32 v195, 1.0, v195
	v_rcp_f32_e32 v28, v188
	v_rcp_f32_e32 v29, v189
	v_rcp_f32_e32 v30, v190
	v_rcp_f32_e32 v31, v191
	v_rcp_f32_e32 v24, v192
	v_rcp_f32_e32 v25, v193
	v_rcp_f32_e32 v26, v194
	v_rcp_f32_e32 v27, v195
	v_pk_mul_f32 v[20:21], v[20:21], v[28:29]
	v_pk_mul_f32 v[22:23], v[22:23], v[30:31]
	v_pk_mul_f32 v[16:17], v[16:17], v[24:25]
	v_pk_mul_f32 v[18:19], v[18:19], v[26:27]
	v_cvt_pk_bf16_f32 v28, v20, v21
	v_cvt_pk_bf16_f32 v29, v22, v23
	v_cvt_pk_bf16_f32 v30, v16, v17
	v_cvt_pk_bf16_f32 v31, v18, v19
	ds_write_b128 v208, v[28:31]
	ds_read_b128 v[200:203], v209
	s_waitcnt lgkmcnt(2)
	global_store_dwordx4 v[146:147], v[204:207], off
	v_lshl_add_u64 v[146:147], v[146:147], 0, s[52:53]
	v_pk_mul_f32 v[12:13], v[12:13], v[240:241] op_sel_hi:[1,0]
	v_pk_mul_f32 v[4:5], v[4:5], v[240:241] op_sel_hi:[1,0]
	v_pk_mul_f32 v[14:15], v[14:15], v[240:241] op_sel_hi:[1,0]
	v_pk_mul_f32 v[6:7], v[6:7], v[240:241] op_sel_hi:[1,0]
	v_pk_mul_f32 v[8:9], v[8:9], v[240:241] op_sel_hi:[1,0]
	v_pk_mul_f32 v[0:1], v[0:1], v[240:241] op_sel_hi:[1,0]
	v_pk_mul_f32 v[10:11], v[10:11], v[240:241] op_sel_hi:[1,0]
	v_pk_mul_f32 v[2:3], v[2:3], v[240:241] op_sel_hi:[1,0]
	v_mul_f32_e32 v188, 0xbfb8aa3b, v12
	v_mul_f32_e32 v189, 0xbfb8aa3b, v13
	v_mul_f32_e32 v190, 0xbfb8aa3b, v14
	v_mul_f32_e32 v191, 0xbfb8aa3b, v15
	v_mul_f32_e32 v192, 0xbfb8aa3b, v8
	v_mul_f32_e32 v193, 0xbfb8aa3b, v9
	v_mul_f32_e32 v194, 0xbfb8aa3b, v10
	v_mul_f32_e32 v195, 0xbfb8aa3b, v11
	v_pk_mul_f32 v[4:5], v[12:13], v[4:5]
	v_pk_mul_f32 v[6:7], v[14:15], v[6:7]
	v_pk_mul_f32 v[0:1], v[8:9], v[0:1]
	v_pk_mul_f32 v[2:3], v[10:11], v[2:3]
	v_exp_f32_e32 v188, v188
	v_exp_f32_e32 v189, v189
	v_exp_f32_e32 v190, v190
	v_exp_f32_e32 v191, v191
	v_exp_f32_e32 v192, v192
	v_exp_f32_e32 v193, v193
	v_exp_f32_e32 v194, v194
	v_exp_f32_e32 v195, v195
	v_add_f32_e32 v188, 1.0, v188
	v_add_f32_e32 v189, 1.0, v189
	v_add_f32_e32 v190, 1.0, v190
	v_add_f32_e32 v191, 1.0, v191
	v_add_f32_e32 v192, 1.0, v192
	v_add_f32_e32 v193, 1.0, v193
	v_add_f32_e32 v194, 1.0, v194
	v_add_f32_e32 v195, 1.0, v195
	v_rcp_f32_e32 v12, v188
	v_rcp_f32_e32 v13, v189
	v_rcp_f32_e32 v14, v190
	v_rcp_f32_e32 v15, v191
	v_rcp_f32_e32 v8, v192
	v_rcp_f32_e32 v9, v193
	v_rcp_f32_e32 v10, v194
	v_rcp_f32_e32 v11, v195
	v_pk_mul_f32 v[4:5], v[4:5], v[12:13]
	v_pk_mul_f32 v[6:7], v[6:7], v[14:15]
	v_pk_mul_f32 v[0:1], v[0:1], v[8:9]
	v_pk_mul_f32 v[2:3], v[2:3], v[10:11]
	v_cvt_pk_bf16_f32 v12, v4, v5
	v_cvt_pk_bf16_f32 v13, v6, v7
	v_cvt_pk_bf16_f32 v14, v0, v1
	v_cvt_pk_bf16_f32 v15, v2, v3
	ds_write_b128 v208, v[12:15]
	ds_read_b128 v[204:207], v209
	s_waitcnt lgkmcnt(2)
	global_store_dwordx4 v[146:147], v[200:203], off
	v_lshl_add_u64 v[146:147], v[146:147], 0, s[52:53]
	s_waitcnt lgkmcnt(0)
	global_store_dwordx4 v[146:147], v[204:207], off
	s_and_b64 vcc, exec, s[2:3]
	s_cbranch_vccz .Lp4_noreduce
	s_waitcnt vmcnt(8)
	v_add_f32_e32 v156, v156, v157
	v_add_f32_e32 v160, v160, v161
	v_add_f32_e32 v164, v164, v165
	v_add_f32_e32 v168, v168, v169
	v_add_f32_e32 v172, v172, v173
	v_add_f32_e32 v176, v176, v177
	v_add_f32_e32 v180, v180, v181
	v_add_f32_e32 v184, v184, v185
	v_add_f32_e32 v158, v158, v159
	v_add_f32_e32 v162, v162, v163
	v_add_f32_e32 v166, v166, v167
	v_add_f32_e32 v170, v170, v171
	v_add_f32_e32 v174, v174, v175
	v_add_f32_e32 v178, v178, v179
	v_add_f32_e32 v182, v182, v183
	v_add_f32_e32 v186, v186, v187
	v_add_f32_e32 v156, v156, v158
	v_add_f32_e32 v160, v160, v162
	v_add_f32_e32 v164, v164, v166
	v_add_f32_e32 v168, v168, v170
	v_add_f32_e32 v172, v172, v174
	v_add_f32_e32 v176, v176, v178
	v_add_f32_e32 v180, v180, v182
	v_add_f32_e32 v184, v184, v186
	v_mov_b32_e32 v157, v156
	v_mov_b32_e32 v161, v160
	v_mov_b32_e32 v165, v164
	v_mov_b32_e32 v169, v168
	v_mov_b32_e32 v173, v172
	v_mov_b32_e32 v177, v176
	v_mov_b32_e32 v181, v180
	v_mov_b32_e32 v185, v184
	v_permlane16_swap_b32_e32 v157, v156
	v_permlane16_swap_b32_e32 v161, v160
	v_permlane16_swap_b32_e32 v165, v164
	v_permlane16_swap_b32_e32 v169, v168
	v_permlane16_swap_b32_e32 v173, v172
	v_permlane16_swap_b32_e32 v177, v176
	v_permlane16_swap_b32_e32 v181, v180
	v_permlane16_swap_b32_e32 v185, v184
	v_add_f32_e32 v156, v156, v157
	v_add_f32_e32 v160, v160, v161
	v_add_f32_e32 v164, v164, v165
	v_add_f32_e32 v168, v168, v169
	v_add_f32_e32 v172, v172, v173
	v_add_f32_e32 v176, v176, v177
	v_add_f32_e32 v180, v180, v181
	v_add_f32_e32 v184, v184, v185
	v_mov_b32_e32 v157, v156
	v_mov_b32_e32 v161, v160
	v_mov_b32_e32 v165, v164
	v_mov_b32_e32 v169, v168
	v_mov_b32_e32 v173, v172
	v_mov_b32_e32 v177, v176
	v_mov_b32_e32 v181, v180
	v_mov_b32_e32 v185, v184
	v_permlane32_swap_b32_e32 v157, v156
	v_permlane32_swap_b32_e32 v161, v160
	v_permlane32_swap_b32_e32 v165, v164
	v_permlane32_swap_b32_e32 v169, v168
	v_permlane32_swap_b32_e32 v173, v172
	v_permlane32_swap_b32_e32 v177, v176
	v_permlane32_swap_b32_e32 v181, v180
	v_permlane32_swap_b32_e32 v185, v184
	v_add_f32_e32 v156, v156, v157
	v_add_f32_e32 v160, v160, v161
	v_add_f32_e32 v164, v164, v165
	v_add_f32_e32 v168, v168, v169
	v_add_f32_e32 v172, v172, v173
	v_add_f32_e32 v176, v176, v177
	v_add_f32_e32 v180, v180, v181
	v_add_f32_e32 v184, v184, v185
	v_fmamk_f32 v156, v156, 0x3a800000, v155
	v_fmamk_f32 v160, v160, 0x3a800000, v155
	v_fmamk_f32 v164, v164, 0x3a800000, v155
	v_fmamk_f32 v168, v168, 0x3a800000, v155
	v_fmamk_f32 v172, v172, 0x3a800000, v155
	v_fmamk_f32 v176, v176, 0x3a800000, v155
	v_fmamk_f32 v180, v180, 0x3a800000, v155
	v_fmamk_f32 v184, v184, 0x3a800000, v155
	v_rsq_f32_e32 v226, v156
	v_rsq_f32_e32 v228, v160
	v_rsq_f32_e32 v230, v164
	v_rsq_f32_e32 v232, v168
	v_rsq_f32_e32 v234, v172
	v_rsq_f32_e32 v236, v176
	v_rsq_f32_e32 v238, v180
	v_rsq_f32_e32 v240, v184
